# attention MFMA segments: 3-4 grouped lgkmcnt waits instead of one per MFMA
# baseline (speedup 1.0000x reference)
.LBB0_1051:
	s_add_i32 s0, s59, 1
	s_cmp_lt_u32 s0, s49
	s_cselect_b64 s[0:1], -1, 0
	s_add_i32 s4, s61, 33
	s_cmp_le_i32 s4, s46
	s_cselect_b64 s[4:5], -1, 0
	s_or_b64 s[4:5], s[18:19], s[4:5]
	s_and_b64 s[0:1], s[0:1], s[4:5]
	s_andn2_b64 vcc, exec, s[0:1]
	s_cbranch_vccnz .LBB0_1053
	s_waitcnt lgkmcnt(5)
	v_mfma_f32_32x32x16_bf16 v[34:49], v[236:239], v[196:199], v[66:81]
	ds_read_b128 v[236:239], v249 offset:6816
	v_mfma_f32_32x32x16_bf16 v[50:65], v[240:243], v[196:199], v[66:81]
	v_mfma_f32_32x32x16_bf16 v[34:49], v[244:247], v[200:203], v[34:49]
	v_mfma_f32_32x32x16_bf16 v[50:65], v[164:167], v[200:203], v[50:65]
	v_mfma_f32_32x32x16_bf16 v[34:49], v[168:171], v[204:207], v[34:49]
	v_mfma_f32_32x32x16_bf16 v[50:65], v[172:175], v[204:207], v[50:65]
	s_waitcnt lgkmcnt(1)
	v_mfma_f32_32x32x16_bf16 v[34:49], v[176:179], v[208:211], v[34:49]
	v_mfma_f32_32x32x16_bf16 v[50:65], v[180:183], v[208:211], v[50:65]
	v_mfma_f32_32x32x16_bf16 v[34:49], v[220:223], v[212:215], v[34:49]
	v_mfma_f32_32x32x16_bf16 v[50:65], v[224:227], v[212:215], v[50:65]
	v_mfma_f32_32x32x16_bf16 v[34:49], v[232:235], v[216:219], v[34:49]
	s_waitcnt lgkmcnt(0)
	v_mfma_f32_32x32x16_bf16 v[50:65], v[236:239], v[216:219], v[50:65]

; template <int DK, int DV>
; __device__ __forceinline__ void attn_unit(LAS unsigned char* lds, const bf16* Qp, int ldq, const bf16* Kp, int ldk, const bf16* VTp, bf16* Op, int ldo, int qb) {
;     ...
;     for (int t = 0; t < NT; t += 2) {
.LBB0_1061:
	s_add_i32 s59, s59, 2
	s_cmp_ge_u32 s59, s49
	s_cselect_b64 s[4:5], -1, 0
	s_cmp_lt_u32 s59, s49
	s_cselect_b64 s[0:1], -1, 0
	s_cmp_lt_i32 s62, -1
	s_cselect_b64 s[18:19], -1, 0
	s_addk_i32 s61, 0x61
	s_cmp_le_i32 s61, s46
	s_cselect_b64 s[20:21], -1, 0
	s_or_b64 s[18:19], s[18:19], s[20:21]
	s_and_b64 s[0:1], s[0:1], s[18:19]
	s_andn2_b64 vcc, exec, s[0:1]
	s_cbranch_vccnz .LBB0_1063
	s_waitcnt lgkmcnt(5)
	v_mfma_f32_32x32x16_bf16 v[34:49], v[236:239], v[196:199], v[66:81]
	ds_read_b128 v[236:239], v249 offset:6816
	v_mfma_f32_32x32x16_bf16 v[50:65], v[240:243], v[196:199], v[66:81]
	v_mfma_f32_32x32x16_bf16 v[34:49], v[244:247], v[200:203], v[34:49]
	v_mfma_f32_32x32x16_bf16 v[50:65], v[164:167], v[200:203], v[50:65]
	v_mfma_f32_32x32x16_bf16 v[34:49], v[168:171], v[204:207], v[34:49]
	v_mfma_f32_32x32x16_bf16 v[50:65], v[172:175], v[204:207], v[50:65]
	s_waitcnt lgkmcnt(1)
	v_mfma_f32_32x32x16_bf16 v[34:49], v[176:179], v[208:211], v[34:49]
	v_mfma_f32_32x32x16_bf16 v[50:65], v[180:183], v[208:211], v[50:65]
	v_mfma_f32_32x32x16_bf16 v[34:49], v[220:223], v[212:215], v[34:49]
	v_mfma_f32_32x32x16_bf16 v[50:65], v[224:227], v[212:215], v[50:65]
	v_mfma_f32_32x32x16_bf16 v[34:49], v[232:235], v[216:219], v[34:49]
	s_waitcnt lgkmcnt(0)
	v_mfma_f32_32x32x16_bf16 v[50:65], v[236:239], v[216:219], v[50:65]

.LBB0_1084:
	s_waitcnt lgkmcnt(0)
	s_barrier
	s_setprio 1
	v_add_u32_e32 v14, s50, v188
	s_waitcnt vmcnt(3)
	ds_write_b128 v14, v[136:139]
	v_add_u32_e32 v14, s50, v186
	v_add_u32_e32 v15, v14, v175
	v_add_u32_e32 v14, v14, v187
	ds_write_b128 v15, v[128:131] offset:9216
	ds_write_b128 v14, v[132:135] offset:9216
	s_and_b64 vcc, exec, s[4:5]
	s_cbranch_vccnz .LBB0_1086
	v_add_u32_e32 v249, s55, v190
	v_mfma_f32_32x32x16_bf16 v[64:79], v[196:199], v[156:159], v[64:79]
	ds_read_b128 v[196:199], v248 offset:9280
	v_mfma_f32_32x32x16_bf16 v[48:63], v[200:203], v[156:159], v[48:63]
	ds_read_b128 v[200:203], v248 offset:13888
	v_mfma_f32_32x32x16_bf16 v[32:47], v[204:207], v[156:159], v[32:47]
	ds_read_b128 v[204:207], v248 offset:18496
	v_mfma_f32_32x32x16_bf16 v[16:31], v[208:211], v[156:159], v[16:31]
	ds_read_b128 v[208:211], v248 offset:23104
	v_mfma_f32_32x32x16_bf16 v[64:79], v[212:215], v[160:163], v[64:79]
	ds_read_b128 v[212:215], v248 offset:9312
	v_mfma_f32_32x32x16_bf16 v[48:63], v[216:219], v[160:163], v[48:63]
	ds_read_b128 v[216:219], v248 offset:13920
	v_mfma_f32_32x32x16_bf16 v[32:47], v[220:223], v[160:163], v[32:47]
	ds_read_b128 v[220:223], v248 offset:18528
	v_mfma_f32_32x32x16_bf16 v[16:31], v[224:227], v[160:163], v[16:31]
	ds_read_b128 v[224:227], v248 offset:23136
	s_waitcnt lgkmcnt(4)
	v_mfma_f32_32x32x16_bf16 v[64:79], v[196:199], v[164:167], v[64:79]
	ds_read_b128 v[196:199], v249
	v_mfma_f32_32x32x16_bf16 v[48:63], v[200:203], v[164:167], v[48:63]
	ds_read_b128 v[200:203], v249 offset:4608
	v_mfma_f32_32x32x16_bf16 v[32:47], v[204:207], v[164:167], v[32:47]
	ds_read_b128 v[204:207], v249 offset:32
	v_mfma_f32_32x32x16_bf16 v[16:31], v[208:211], v[164:167], v[16:31]
	ds_read_b128 v[208:211], v249 offset:4640
	s_waitcnt lgkmcnt(4)
	v_mfma_f32_32x32x16_bf16 v[64:79], v[212:215], v[168:171], v[64:79]
	ds_read_b128 v[212:215], v249 offset:64
	v_mfma_f32_32x32x16_bf16 v[48:63], v[216:219], v[168:171], v[48:63]
	ds_read_b128 v[216:219], v249 offset:4672
	v_mfma_f32_32x32x16_bf16 v[32:47], v[220:223], v[168:171], v[32:47]
	ds_read_b128 v[220:223], v249 offset:96
	v_mfma_f32_32x32x16_bf16 v[16:31], v[224:227], v[168:171], v[16:31]
	ds_read_b128 v[224:227], v249 offset:4704
.LBB0_1086:
	s_add_i32 s0, s54, 1
	s_cmp_lt_u32 s0, s44
	s_cselect_b64 s[0:1], -1, 0
	s_add_i32 s4, s56, 33
	s_cmp_le_i32 s4, s35
	s_cselect_b64 s[4:5], -1, 0
	s_or_b64 s[4:5], s[16:17], s[4:5]
	s_and_b64 s[0:1], s[0:1], s[4:5]
	s_andn2_b64 vcc, exec, s[0:1]
	v_add_u32_e32 v0, s55, v190
	s_cbranch_vccnz .LBB0_1088
	s_waitcnt lgkmcnt(4)
	v_mfma_f32_32x32x16_bf16 v[80:95], v[196:199], v[232:235], v[112:127]
	v_mfma_f32_32x32x16_bf16 v[96:111], v[200:203], v[232:235], v[112:127]
	v_mfma_f32_32x32x16_bf16 v[80:95], v[204:207], v[236:239], v[80:95]
	v_mfma_f32_32x32x16_bf16 v[96:111], v[208:211], v[236:239], v[96:111]
	s_waitcnt lgkmcnt(0)
	v_mfma_f32_32x32x16_bf16 v[80:95], v[212:215], v[240:243], v[80:95]
	v_mfma_f32_32x32x16_bf16 v[96:111], v[216:219], v[240:243], v[96:111]
	v_mfma_f32_32x32x16_bf16 v[80:95], v[220:223], v[244:247], v[80:95]
	v_mfma_f32_32x32x16_bf16 v[96:111], v[224:227], v[244:247], v[96:111]

.LBB0_1094:
	s_waitcnt lgkmcnt(0)
	s_barrier
	s_setprio 1
	v_add_u32_e32 v0, s51, v188
	s_waitcnt vmcnt(5)
	ds_write_b128 v0, v[10:13]
	v_add_u32_e32 v0, s51, v186
	v_add_u32_e32 v10, v0, v175
	v_add_u32_e32 v0, v0, v187
	s_waitcnt vmcnt(4)
	ds_write_b128 v10, v[2:5] offset:9216
	s_waitcnt vmcnt(3)
	ds_write_b128 v0, v[6:9] offset:9216
	s_and_b64 vcc, exec, s[4:5]
	s_cbranch_vccnz .LBB0_1096
	v_add_u32_e32 v249, s50, v190
	v_mfma_f32_32x32x16_bf16 v[64:79], v[196:199], v[140:143], v[64:79]
	ds_read_b128 v[196:199], v248 offset:9280
	v_mfma_f32_32x32x16_bf16 v[48:63], v[200:203], v[140:143], v[48:63]
	ds_read_b128 v[200:203], v248 offset:13888
	v_mfma_f32_32x32x16_bf16 v[32:47], v[204:207], v[140:143], v[32:47]
	ds_read_b128 v[204:207], v248 offset:18496
	v_mfma_f32_32x32x16_bf16 v[16:31], v[208:211], v[140:143], v[16:31]
	ds_read_b128 v[208:211], v248 offset:23104
	v_mfma_f32_32x32x16_bf16 v[64:79], v[212:215], v[144:147], v[64:79]
	ds_read_b128 v[212:215], v248 offset:9312
	v_mfma_f32_32x32x16_bf16 v[48:63], v[216:219], v[144:147], v[48:63]
	ds_read_b128 v[216:219], v248 offset:13920
	v_mfma_f32_32x32x16_bf16 v[32:47], v[220:223], v[144:147], v[32:47]
	ds_read_b128 v[220:223], v248 offset:18528
	v_mfma_f32_32x32x16_bf16 v[16:31], v[224:227], v[144:147], v[16:31]
	ds_read_b128 v[224:227], v248 offset:23136
	s_waitcnt lgkmcnt(4)
	v_mfma_f32_32x32x16_bf16 v[64:79], v[196:199], v[148:151], v[64:79]
	ds_read_b128 v[196:199], v249
	v_mfma_f32_32x32x16_bf16 v[48:63], v[200:203], v[148:151], v[48:63]
	ds_read_b128 v[200:203], v249 offset:4608
	v_mfma_f32_32x32x16_bf16 v[32:47], v[204:207], v[148:151], v[32:47]
	ds_read_b128 v[204:207], v249 offset:32
	v_mfma_f32_32x32x16_bf16 v[16:31], v[208:211], v[148:151], v[16:31]
	ds_read_b128 v[208:211], v249 offset:4640
	s_waitcnt lgkmcnt(4)
	v_mfma_f32_32x32x16_bf16 v[64:79], v[212:215], v[152:155], v[64:79]
	ds_read_b128 v[212:215], v249 offset:64
	v_mfma_f32_32x32x16_bf16 v[48:63], v[216:219], v[152:155], v[48:63]
	ds_read_b128 v[216:219], v249 offset:4672
	v_mfma_f32_32x32x16_bf16 v[32:47], v[220:223], v[152:155], v[32:47]
	ds_read_b128 v[220:223], v249 offset:96
	v_mfma_f32_32x32x16_bf16 v[16:31], v[224:227], v[152:155], v[16:31]
	ds_read_b128 v[224:227], v249 offset:4704
.LBB0_1096:
	s_add_i32 s54, s54, 2
	s_cmp_ge_u32 s54, s44
	s_cselect_b64 s[4:5], -1, 0
	s_cmp_lt_u32 s54, s44
	s_cselect_b64 s[0:1], -1, 0
	s_cmp_lt_i32 s57, -1
	s_cselect_b64 s[16:17], -1, 0
	s_addk_i32 s56, 0x61
	s_cmp_le_i32 s56, s35
	s_cselect_b64 s[18:19], -1, 0
	s_or_b64 s[16:17], s[16:17], s[18:19]
	s_and_b64 s[0:1], s[0:1], s[16:17]
	s_andn2_b64 vcc, exec, s[0:1]
	s_cbranch_vccnz .LBB0_1098
	s_waitcnt lgkmcnt(4)
	v_mfma_f32_32x32x16_bf16 v[80:95], v[196:199], v[232:235], v[112:127]
	v_mfma_f32_32x32x16_bf16 v[96:111], v[200:203], v[232:235], v[112:127]
	v_mfma_f32_32x32x16_bf16 v[80:95], v[204:207], v[236:239], v[80:95]
	v_mfma_f32_32x32x16_bf16 v[96:111], v[208:211], v[236:239], v[96:111]
	s_waitcnt lgkmcnt(0)
	v_mfma_f32_32x32x16_bf16 v[80:95], v[212:215], v[240:243], v[80:95]
	v_mfma_f32_32x32x16_bf16 v[96:111], v[216:219], v[240:243], v[96:111]
	v_mfma_f32_32x32x16_bf16 v[80:95], v[220:223], v[244:247], v[80:95]
	v_mfma_f32_32x32x16_bf16 v[96:111], v[224:227], v[244:247], v[96:111]
